# SwiGLU epilogue: packed f32 VALU split into scalar pairs (packed-vs-scalar issue cost test)
# baseline (speedup 1.0000x reference)
; #define LAS __attribute__((address_space(3)))
; __device__ __forceinline__ unsigned cvt_pk2(float lo, float hi) { f32x2c v = {lo, hi}; bf16x2c q = __builtin_convertvector(v, bf16x2c); return __builtin_bit_cast(unsigned, q); }
;     __device__ __forceinline__ void operator()(const f32x4 (&acc)[2][2][4][2], const pg8::Unit& u, int wr, int wc, int fr, int fq) const {
;         const int row0 = u.pm * 256 + wr * 64 + fr, col0 = u.pn * 128 + wc * 32 + 8 * fq;
;         const LAS float* rt = rt_.of(u.pm) + wr * 64 + fr;
; #pragma unroll
;         for (int ai = 0; ai < 2; ++ai)
; #pragma unroll
;             for (int m = 0; m < 4; ++m) { bf16_t* rowp = O + (size_t)(row0 + ai * 128 + m * 16) * FF + col0; const float r = rt[ai * 128 + m * 16];
;                 const float rl = -r * LOG2E, r2 = r * r; unsigned w[4];
; #pragma unroll
;                 for (int n = 0; n < 2; ++n)
; #pragma unroll
;                     for (int h = 0; h < 2; ++h) { const f32x2v g = {acc[ai][0][m][n][2 * h], acc[ai][0][m][n][2 * h + 1]}, uu = {acc[ai][1][m][n][2 * h], acc[ai][1][m][n][2 * h + 1]};
;                         const f32x2v t = g * rl; f32x2v d = {__builtin_amdgcn_exp2f(t.x), __builtin_amdgcn_exp2f(t.y)}; d = d + 1.0f;
;                         const f32x2v q = {__builtin_amdgcn_rcpf(d.x), __builtin_amdgcn_rcpf(d.y)}; const f32x2v o = ((g * uu) * r2) * q;
;                         w[2 * n + h] = cvt_pk2(o.x, o.y); }
;                 u32x4 wv; wv.x = w[0]; wv.y = w[1]; wv.z = w[2]; wv.w = w[3];
;                 *(u32x4*)rowp = wv; }
.LBB0_227:
	s_cmp_eq_u32 s34, s51
	s_cselect_b32 s13, s65, 0x300
	s_cmp_lg_u32 s34, s52
	s_cselect_b32 s13, s13, 0x100
	s_cmp_lg_u32 s34, s50
	s_cselect_b32 s13, s13, 0
	v_lshl_add_u32 v154, s13, 2, v148
	ds_read2_b32 v[200:201], v154 offset1:16
	ds_read2_b32 v[202:203], v154 offset0:32 offset1:48
	ds_read2_b32 v[204:205], v154 offset0:128 offset1:144
	ds_read2_b32 v[206:207], v154 offset0:160 offset1:176
	v_lshl_add_u32 v153, s34, 8, v146
	v_lshl_or_b32 v158, s67, 7, v149
	v_mov_b64_e32 v[178:179], s[40:41]
	s_mov_b32 s98, 0x1600
	v_lshlrev_b32_e32 v158, 1, v158
	v_mov_b32_e32 v159, 0
	v_mad_i64_i32 v[178:179], s[20:21], v153, s98, v[178:179]
	s_mov_b32 s98, 0x16000
	s_mov_b32 s99, 0
	s_mov_b32 s100, 0x6e000
	s_mov_b32 s101, 0
	v_lshl_add_u64 v[178:179], v[178:179], 0, v[158:159]
	s_waitcnt lgkmcnt(0)
	v_mul_f32_e32 v208, 0xbfb8aa3b, v200
	v_mul_f32_e32 v228, v200, v200
	v_mul_f32_e32 v210, 0xbfb8aa3b, v201
	v_mul_f32_e32 v230, v201, v201
	v_mul_f32_e32 v212, 0xbfb8aa3b, v202
	v_mul_f32_e32 v232, v202, v202
	v_mul_f32_e32 v214, 0xbfb8aa3b, v203
	v_mul_f32_e32 v234, v203, v203
	v_mul_f32_e32 v216, 0xbfb8aa3b, v204
	v_mul_f32_e32 v236, v204, v204
	v_mul_f32_e32 v218, 0xbfb8aa3b, v205
	v_mul_f32_e32 v238, v205, v205
	v_mul_f32_e32 v220, 0xbfb8aa3b, v206
	v_mul_f32_e32 v240, v206, v206
	v_mul_f32_e32 v222, 0xbfb8aa3b, v207
	v_mul_f32_e32 v242, v207, v207
	v_rcp_f32_e32 v228, v228
	v_rcp_f32_e32 v230, v230
	v_rcp_f32_e32 v232, v232
	v_rcp_f32_e32 v234, v234
	v_rcp_f32_e32 v236, v236
	v_rcp_f32_e32 v238, v238
	v_rcp_f32_e32 v240, v240
	v_rcp_f32_e32 v242, v242
	v_mul_f32_e32 v154, v124, v208
	v_mul_f32_e32 v155, v125, v208
	v_mul_f32_e32 v156, v126, v208
	v_mul_f32_e32 v157, v127, v208
	v_mul_f32_e32 v158, v116, v208
	v_mul_f32_e32 v159, v117, v208
	v_mul_f32_e32 v160, v118, v208
	v_mul_f32_e32 v161, v119, v208
	v_exp_f32_e32 v154, v154
	v_exp_f32_e32 v155, v155
	v_exp_f32_e32 v156, v156
	v_exp_f32_e32 v157, v157
	v_exp_f32_e32 v158, v158
	v_exp_f32_e32 v159, v159
	v_exp_f32_e32 v160, v160
	v_exp_f32_e32 v161, v161
	v_mul_f32_e32 v162, v108, v210
	v_mul_f32_e32 v163, v109, v210
	v_mul_f32_e32 v164, v110, v210
	v_mul_f32_e32 v165, v111, v210
	v_mul_f32_e32 v166, v100, v210
	v_mul_f32_e32 v167, v101, v210
	v_mul_f32_e32 v168, v102, v210
	v_mul_f32_e32 v169, v103, v210
	v_exp_f32_e32 v162, v162
	v_exp_f32_e32 v163, v163
	v_exp_f32_e32 v164, v164
	v_exp_f32_e32 v165, v165
	v_exp_f32_e32 v166, v166
	v_exp_f32_e32 v167, v167
	v_exp_f32_e32 v168, v168
	v_exp_f32_e32 v169, v169
	v_mul_f32_e32 v120, v124, v120
	v_mul_f32_e32 v121, v125, v121
	v_mul_f32_e32 v122, v126, v122
	v_mul_f32_e32 v123, v127, v123
	v_mul_f32_e32 v112, v116, v112
	v_mul_f32_e32 v113, v117, v113
	v_mul_f32_e32 v114, v118, v114
	v_mul_f32_e32 v115, v119, v115
	v_fma_f32 v154, v154, v228, v228
	v_fma_f32 v155, v155, v228, v228
	v_fma_f32 v156, v156, v228, v228
	v_fma_f32 v157, v157, v228, v228
	v_fma_f32 v158, v158, v228, v228
	v_fma_f32 v159, v159, v228, v228
	v_fma_f32 v160, v160, v228, v228
	v_fma_f32 v161, v161, v228, v228
	v_rcp_f32_e32 v154, v154
	v_rcp_f32_e32 v155, v155
	v_rcp_f32_e32 v156, v156
	v_rcp_f32_e32 v157, v157
	v_rcp_f32_e32 v158, v158
	v_rcp_f32_e32 v159, v159
	v_rcp_f32_e32 v160, v160
	v_rcp_f32_e32 v161, v161
	v_mul_f32_e32 v170, v92, v212
	v_mul_f32_e32 v171, v93, v212
	v_mul_f32_e32 v172, v94, v212
	v_mul_f32_e32 v173, v95, v212
	v_mul_f32_e32 v174, v84, v212
	v_mul_f32_e32 v175, v85, v212
	v_mul_f32_e32 v176, v86, v212
	v_mul_f32_e32 v177, v87, v212
	v_exp_f32_e32 v170, v170
	v_exp_f32_e32 v171, v171
	v_exp_f32_e32 v172, v172
	v_exp_f32_e32 v173, v173
	v_exp_f32_e32 v174, v174
	v_exp_f32_e32 v175, v175
	v_exp_f32_e32 v176, v176
	v_exp_f32_e32 v177, v177
	v_mul_f32_e32 v104, v108, v104
	v_mul_f32_e32 v105, v109, v105
	v_mul_f32_e32 v106, v110, v106
	v_mul_f32_e32 v107, v111, v107
	v_mul_f32_e32 v96, v100, v96
	v_mul_f32_e32 v97, v101, v97
	v_mul_f32_e32 v98, v102, v98
	v_mul_f32_e32 v99, v103, v99
	v_fma_f32 v162, v162, v230, v230
	v_fma_f32 v163, v163, v230, v230
	v_fma_f32 v164, v164, v230, v230
	v_fma_f32 v165, v165, v230, v230
	v_fma_f32 v166, v166, v230, v230
	v_fma_f32 v167, v167, v230, v230
	v_fma_f32 v168, v168, v230, v230
	v_fma_f32 v169, v169, v230, v230
	v_rcp_f32_e32 v162, v162
	v_rcp_f32_e32 v163, v163
	v_rcp_f32_e32 v164, v164
	v_rcp_f32_e32 v165, v165
	v_rcp_f32_e32 v166, v166
	v_rcp_f32_e32 v167, v167
	v_rcp_f32_e32 v168, v168
	v_rcp_f32_e32 v169, v169
	v_mul_f32_e32 v120, v120, v154
	v_mul_f32_e32 v121, v121, v155
	v_mul_f32_e32 v122, v122, v156
	v_mul_f32_e32 v123, v123, v157
	v_mul_f32_e32 v112, v112, v158
	v_mul_f32_e32 v113, v113, v159
	v_mul_f32_e32 v114, v114, v160
	v_mul_f32_e32 v115, v115, v161
	v_cvt_pk_bf16_f32 v154, v120, v121
	v_cvt_pk_bf16_f32 v155, v122, v123
	v_cvt_pk_bf16_f32 v156, v112, v113
	v_cvt_pk_bf16_f32 v157, v114, v115
	global_store_dwordx4 v[178:179], v[154:157], off
	v_lshl_add_u64 v[178:179], v[178:179], 0, s[98:99]
	s_nop 1
	v_mul_f32_e32 v154, v76, v214
	v_mul_f32_e32 v155, v77, v214
	v_mul_f32_e32 v156, v78, v214
	v_mul_f32_e32 v157, v79, v214
	v_mul_f32_e32 v158, v68, v214
	v_mul_f32_e32 v159, v69, v214
	v_mul_f32_e32 v160, v70, v214
	v_mul_f32_e32 v161, v71, v214
	v_exp_f32_e32 v154, v154
	v_exp_f32_e32 v155, v155
	v_exp_f32_e32 v156, v156
	v_exp_f32_e32 v157, v157
	v_exp_f32_e32 v158, v158
	v_exp_f32_e32 v159, v159
	v_exp_f32_e32 v160, v160
	v_exp_f32_e32 v161, v161
	v_mul_f32_e32 v88, v92, v88
	v_mul_f32_e32 v89, v93, v89
	v_mul_f32_e32 v90, v94, v90
	v_mul_f32_e32 v91, v95, v91
	v_mul_f32_e32 v80, v84, v80
	v_mul_f32_e32 v81, v85, v81
	v_mul_f32_e32 v82, v86, v82
	v_mul_f32_e32 v83, v87, v83
; __device__ __forceinline__ unsigned cvt_pk2(float lo, float hi) { f32x2c v = {lo, hi}; bf16x2c q = __builtin_convertvector(v, bf16x2c); return __builtin_bit_cast(unsigned, q); }
;     __device__ __forceinline__ void operator()(const f32x4 (&acc)[2][2][4][2], const pg8::Unit& u, int wr, int wc, int fr, int fq) const {
;     ...
;             for (int m = 0; m < 4; ++m) { bf16_t* rowp = O + (size_t)(row0 + ai * 128 + m * 16) * FF + col0; const float r = rt[ai * 128 + m * 16];
;                 const float rl = -r * LOG2E, r2 = r * r; unsigned w[4];
; #pragma unroll
;                 for (int n = 0; n < 2; ++n)
; #pragma unroll
;                     for (int h = 0; h < 2; ++h) { const f32x2v g = {acc[ai][0][m][n][2 * h], acc[ai][0][m][n][2 * h + 1]}, uu = {acc[ai][1][m][n][2 * h], acc[ai][1][m][n][2 * h + 1]};
;                         const f32x2v t = g * rl; f32x2v d = {__builtin_amdgcn_exp2f(t.x), __builtin_amdgcn_exp2f(t.y)}; d = d + 1.0f;
;                         const f32x2v q = {__builtin_amdgcn_rcpf(d.x), __builtin_amdgcn_rcpf(d.y)}; const f32x2v o = ((g * uu) * r2) * q;
;                         w[2 * n + h] = cvt_pk2(o.x, o.y); }
;                 u32x4 wv; wv.x = w[0]; wv.y = w[1]; wv.z = w[2]; wv.w = w[3];
;                 *(u32x4*)rowp = wv; }
	v_fma_f32 v170, v170, v232, v232
	v_fma_f32 v171, v171, v232, v232
	v_fma_f32 v172, v172, v232, v232
	v_fma_f32 v173, v173, v232, v232
	v_fma_f32 v174, v174, v232, v232
	v_fma_f32 v175, v175, v232, v232
	v_fma_f32 v176, v176, v232, v232
	v_fma_f32 v177, v177, v232, v232
	v_rcp_f32_e32 v170, v170
	v_rcp_f32_e32 v171, v171
	v_rcp_f32_e32 v172, v172
	v_rcp_f32_e32 v173, v173
	v_rcp_f32_e32 v174, v174
	v_rcp_f32_e32 v175, v175
	v_rcp_f32_e32 v176, v176
	v_rcp_f32_e32 v177, v177
	v_mul_f32_e32 v104, v104, v162
	v_mul_f32_e32 v105, v105, v163
	v_mul_f32_e32 v106, v106, v164
	v_mul_f32_e32 v107, v107, v165
	v_mul_f32_e32 v96, v96, v166
	v_mul_f32_e32 v97, v97, v167
	v_mul_f32_e32 v98, v98, v168
	v_mul_f32_e32 v99, v99, v169
	v_cvt_pk_bf16_f32 v162, v104, v105
	v_cvt_pk_bf16_f32 v163, v106, v107
	v_cvt_pk_bf16_f32 v164, v96, v97
	v_cvt_pk_bf16_f32 v165, v98, v99
	global_store_dwordx4 v[178:179], v[162:165], off
	v_lshl_add_u64 v[178:179], v[178:179], 0, s[98:99]
	s_nop 1
	v_mul_f32_e32 v162, v60, v216
	v_mul_f32_e32 v163, v61, v216
	v_mul_f32_e32 v164, v62, v216
	v_mul_f32_e32 v165, v63, v216
	v_mul_f32_e32 v166, v52, v216
	v_mul_f32_e32 v167, v53, v216
	v_mul_f32_e32 v168, v54, v216
	v_mul_f32_e32 v169, v55, v216
	v_exp_f32_e32 v162, v162
	v_exp_f32_e32 v163, v163
	v_exp_f32_e32 v164, v164
	v_exp_f32_e32 v165, v165
	v_exp_f32_e32 v166, v166
	v_exp_f32_e32 v167, v167
	v_exp_f32_e32 v168, v168
	v_exp_f32_e32 v169, v169
	v_mul_f32_e32 v72, v76, v72
	v_mul_f32_e32 v73, v77, v73
	v_mul_f32_e32 v74, v78, v74
	v_mul_f32_e32 v75, v79, v75
	v_mul_f32_e32 v64, v68, v64
	v_mul_f32_e32 v65, v69, v65
	v_mul_f32_e32 v66, v70, v66
	v_mul_f32_e32 v67, v71, v67
	v_fma_f32 v154, v154, v234, v234
	v_fma_f32 v155, v155, v234, v234
	v_fma_f32 v156, v156, v234, v234
	v_fma_f32 v157, v157, v234, v234
	v_fma_f32 v158, v158, v234, v234
	v_fma_f32 v159, v159, v234, v234
	v_fma_f32 v160, v160, v234, v234
	v_fma_f32 v161, v161, v234, v234
	v_rcp_f32_e32 v154, v154
	v_rcp_f32_e32 v155, v155
	v_rcp_f32_e32 v156, v156
	v_rcp_f32_e32 v157, v157
	v_rcp_f32_e32 v158, v158
	v_rcp_f32_e32 v159, v159
	v_rcp_f32_e32 v160, v160
	v_rcp_f32_e32 v161, v161
	v_mul_f32_e32 v88, v88, v170
	v_mul_f32_e32 v89, v89, v171
	v_mul_f32_e32 v90, v90, v172
	v_mul_f32_e32 v91, v91, v173
	v_mul_f32_e32 v80, v80, v174
	v_mul_f32_e32 v81, v81, v175
	v_mul_f32_e32 v82, v82, v176
	v_mul_f32_e32 v83, v83, v177
	v_cvt_pk_bf16_f32 v170, v88, v89
	v_cvt_pk_bf16_f32 v171, v90, v91
	v_cvt_pk_bf16_f32 v172, v80, v81
	v_cvt_pk_bf16_f32 v173, v82, v83
	global_store_dwordx4 v[178:179], v[170:173], off
	v_lshl_add_u64 v[178:179], v[178:179], 0, s[98:99]
	s_nop 1
	v_mul_f32_e32 v170, v44, v218
	v_mul_f32_e32 v171, v45, v218
	v_mul_f32_e32 v172, v46, v218
	v_mul_f32_e32 v173, v47, v218
	v_mul_f32_e32 v174, v36, v218
	v_mul_f32_e32 v175, v37, v218
	v_mul_f32_e32 v176, v38, v218
	v_mul_f32_e32 v177, v39, v218
	v_exp_f32_e32 v170, v170
	v_exp_f32_e32 v171, v171
	v_exp_f32_e32 v172, v172
	v_exp_f32_e32 v173, v173
	v_exp_f32_e32 v174, v174
	v_exp_f32_e32 v175, v175
	v_exp_f32_e32 v176, v176
	v_exp_f32_e32 v177, v177
	v_mul_f32_e32 v56, v60, v56
	v_mul_f32_e32 v57, v61, v57
	v_mul_f32_e32 v58, v62, v58
	v_mul_f32_e32 v59, v63, v59
	v_mul_f32_e32 v48, v52, v48
	v_mul_f32_e32 v49, v53, v49
	v_mul_f32_e32 v50, v54, v50
	v_mul_f32_e32 v51, v55, v51
	v_fma_f32 v162, v162, v236, v236
	v_fma_f32 v163, v163, v236, v236
	v_fma_f32 v164, v164, v236, v236
	v_fma_f32 v165, v165, v236, v236
	v_fma_f32 v166, v166, v236, v236
	v_fma_f32 v167, v167, v236, v236
	v_fma_f32 v168, v168, v236, v236
	v_fma_f32 v169, v169, v236, v236
	v_rcp_f32_e32 v162, v162
	v_rcp_f32_e32 v163, v163
	v_rcp_f32_e32 v164, v164
	v_rcp_f32_e32 v165, v165
	v_rcp_f32_e32 v166, v166
	v_rcp_f32_e32 v167, v167
	v_rcp_f32_e32 v168, v168
	v_rcp_f32_e32 v169, v169
	v_mul_f32_e32 v72, v72, v154
	v_mul_f32_e32 v73, v73, v155
	v_mul_f32_e32 v74, v74, v156
	v_mul_f32_e32 v75, v75, v157
	v_mul_f32_e32 v64, v64, v158
	v_mul_f32_e32 v65, v65, v159
	v_mul_f32_e32 v66, v66, v160
	v_mul_f32_e32 v67, v67, v161
	v_cvt_pk_bf16_f32 v154, v72, v73
	v_cvt_pk_bf16_f32 v155, v74, v75
	v_cvt_pk_bf16_f32 v156, v64, v65
	v_cvt_pk_bf16_f32 v157, v66, v67
	global_store_dwordx4 v[178:179], v[154:157], off
	v_lshl_add_u64 v[178:179], v[178:179], 0, s[100:101]
	s_nop 1
	v_mul_f32_e32 v154, v28, v220
	v_mul_f32_e32 v155, v29, v220
	v_mul_f32_e32 v156, v30, v220
	v_mul_f32_e32 v157, v31, v220
	v_mul_f32_e32 v158, v20, v220
	v_mul_f32_e32 v159, v21, v220
	v_mul_f32_e32 v160, v22, v220
	v_mul_f32_e32 v161, v23, v220
	v_exp_f32_e32 v154, v154
	v_exp_f32_e32 v155, v155
	v_exp_f32_e32 v156, v156
	v_exp_f32_e32 v157, v157
	v_exp_f32_e32 v158, v158
; #define PG8_BAR __builtin_amdgcn_s_barrier()
; __device__ __forceinline__ unsigned cvt_pk2(float lo, float hi) { f32x2c v = {lo, hi}; bf16x2c q = __builtin_convertvector(v, bf16x2c); return __builtin_bit_cast(unsigned, q); }
; template <class Epi, class Sched, bool ALIGN_EPI = false, bool SP2 = false>
; __device__ __forceinline__ void gemm_phase(PG8_LAS unsigned char* lds, const Gemm g, const Sched& S, const Epi& E) {
;     ...
;         if (!has_next) break;
; #pragma unroll
;         for (int a = 0; a < 2; ++a)
; #pragma unroll
;             for (int b = 0; b < 2; ++b)
; #pragma unroll
;                 for (int m = 0; m < 4; ++m)
; #pragma unroll
;                     for (int n = 0; n < 2; ++n) acc[a][b][m][n] = (f32x4){0.f, 0.f, 0.f, 0.f};
;         cur = nxt; cA = nA; cB = nB; ++ui;
;         if constexpr (ALIGN_EPI) { if (wr == 1) PG8_BAR; }
;     __device__ __forceinline__ void operator()(const f32x4 (&acc)[2][2][4][2], const pg8::Unit& u, int wr, int wc, int fr, int fq) const {
;     ...
;             for (int m = 0; m < 4; ++m) { bf16_t* rowp = O + (size_t)(row0 + ai * 128 + m * 16) * FF + col0; const float r = rt[ai * 128 + m * 16];
;                 const float rl = -r * LOG2E, r2 = r * r; unsigned w[4];
; #pragma unroll
;                 for (int n = 0; n < 2; ++n)
; #pragma unroll
;                     for (int h = 0; h < 2; ++h) { const f32x2v g = {acc[ai][0][m][n][2 * h], acc[ai][0][m][n][2 * h + 1]}, uu = {acc[ai][1][m][n][2 * h], acc[ai][1][m][n][2 * h + 1]};
;                         const f32x2v t = g * rl; f32x2v d = {__builtin_amdgcn_exp2f(t.x), __builtin_amdgcn_exp2f(t.y)}; d = d + 1.0f;
;                         const f32x2v q = {__builtin_amdgcn_rcpf(d.x), __builtin_amdgcn_rcpf(d.y)}; const f32x2v o = ((g * uu) * r2) * q;
;                         w[2 * n + h] = cvt_pk2(o.x, o.y); }
;                 u32x4 wv; wv.x = w[0]; wv.y = w[1]; wv.z = w[2]; wv.w = w[3];
;                 *(u32x4*)rowp = wv; }
	v_exp_f32_e32 v159, v159
	v_exp_f32_e32 v160, v160
	v_exp_f32_e32 v161, v161
	v_mul_f32_e32 v40, v44, v40
	v_mul_f32_e32 v41, v45, v41
	v_mul_f32_e32 v42, v46, v42
	v_mul_f32_e32 v43, v47, v43
	v_mul_f32_e32 v32, v36, v32
	v_mul_f32_e32 v33, v37, v33
	v_mul_f32_e32 v34, v38, v34
	v_mul_f32_e32 v35, v39, v35
	v_fma_f32 v170, v170, v238, v238
	v_fma_f32 v171, v171, v238, v238
	v_fma_f32 v172, v172, v238, v238
	v_fma_f32 v173, v173, v238, v238
	v_fma_f32 v174, v174, v238, v238
	v_fma_f32 v175, v175, v238, v238
	v_fma_f32 v176, v176, v238, v238
	v_fma_f32 v177, v177, v238, v238
	v_rcp_f32_e32 v170, v170
	v_rcp_f32_e32 v171, v171
	v_rcp_f32_e32 v172, v172
	v_rcp_f32_e32 v173, v173
	v_rcp_f32_e32 v174, v174
	v_rcp_f32_e32 v175, v175
	v_rcp_f32_e32 v176, v176
	v_rcp_f32_e32 v177, v177
	v_mul_f32_e32 v56, v56, v162
	v_mul_f32_e32 v57, v57, v163
	v_mul_f32_e32 v58, v58, v164
	v_mul_f32_e32 v59, v59, v165
	v_mul_f32_e32 v48, v48, v166
	v_mul_f32_e32 v49, v49, v167
	v_mul_f32_e32 v50, v50, v168
	v_mul_f32_e32 v51, v51, v169
	v_cvt_pk_bf16_f32 v162, v56, v57
	v_cvt_pk_bf16_f32 v163, v58, v59
	v_cvt_pk_bf16_f32 v164, v48, v49
	v_cvt_pk_bf16_f32 v165, v50, v51
	global_store_dwordx4 v[178:179], v[162:165], off
	v_lshl_add_u64 v[178:179], v[178:179], 0, s[98:99]
	s_nop 1
	v_mul_f32_e32 v162, v12, v222
	v_mul_f32_e32 v163, v13, v222
	v_mul_f32_e32 v164, v14, v222
	v_mul_f32_e32 v165, v15, v222
	v_mul_f32_e32 v166, v4, v222
	v_mul_f32_e32 v167, v5, v222
	v_mul_f32_e32 v168, v6, v222
	v_mul_f32_e32 v169, v7, v222
	v_exp_f32_e32 v162, v162
	v_exp_f32_e32 v163, v163
	v_exp_f32_e32 v164, v164
	v_exp_f32_e32 v165, v165
	v_exp_f32_e32 v166, v166
	v_exp_f32_e32 v167, v167
	v_exp_f32_e32 v168, v168
	v_exp_f32_e32 v169, v169
	v_mul_f32_e32 v24, v28, v24
	v_mul_f32_e32 v25, v29, v25
	v_mul_f32_e32 v26, v30, v26
	v_mul_f32_e32 v27, v31, v27
	v_mul_f32_e32 v16, v20, v16
	v_mul_f32_e32 v17, v21, v17
	v_mul_f32_e32 v18, v22, v18
	v_mul_f32_e32 v19, v23, v19
	v_fma_f32 v154, v154, v240, v240
	v_fma_f32 v155, v155, v240, v240
	v_fma_f32 v156, v156, v240, v240
	v_fma_f32 v157, v157, v240, v240
	v_fma_f32 v158, v158, v240, v240
	v_fma_f32 v159, v159, v240, v240
	v_fma_f32 v160, v160, v240, v240
	v_fma_f32 v161, v161, v240, v240
	v_rcp_f32_e32 v154, v154
	v_rcp_f32_e32 v155, v155
	v_rcp_f32_e32 v156, v156
	v_rcp_f32_e32 v157, v157
	v_rcp_f32_e32 v158, v158
	v_rcp_f32_e32 v159, v159
	v_rcp_f32_e32 v160, v160
	v_rcp_f32_e32 v161, v161
	v_mul_f32_e32 v40, v40, v170
	v_mul_f32_e32 v41, v41, v171
	v_mul_f32_e32 v42, v42, v172
	v_mul_f32_e32 v43, v43, v173
	v_mul_f32_e32 v32, v32, v174
	v_mul_f32_e32 v33, v33, v175
	v_mul_f32_e32 v34, v34, v176
	v_mul_f32_e32 v35, v35, v177
	v_cvt_pk_bf16_f32 v170, v40, v41
	v_cvt_pk_bf16_f32 v171, v42, v43
	v_cvt_pk_bf16_f32 v172, v32, v33
	v_cvt_pk_bf16_f32 v173, v34, v35
	global_store_dwordx4 v[178:179], v[170:173], off
	v_lshl_add_u64 v[178:179], v[178:179], 0, s[98:99]
	s_nop 1
	v_mul_f32_e32 v8, v12, v8
	v_mul_f32_e32 v9, v13, v9
	v_mul_f32_e32 v10, v14, v10
	v_mul_f32_e32 v11, v15, v11
	v_mul_f32_e32 v0, v4, v0
	v_mul_f32_e32 v1, v5, v1
	v_mul_f32_e32 v2, v6, v2
	v_mul_f32_e32 v3, v7, v3
	v_fma_f32 v162, v162, v242, v242
	v_fma_f32 v163, v163, v242, v242
	v_fma_f32 v164, v164, v242, v242
	v_fma_f32 v165, v165, v242, v242
	v_fma_f32 v166, v166, v242, v242
	v_fma_f32 v167, v167, v242, v242
	v_fma_f32 v168, v168, v242, v242
	v_fma_f32 v169, v169, v242, v242
	v_rcp_f32_e32 v162, v162
	v_rcp_f32_e32 v163, v163
	v_rcp_f32_e32 v164, v164
	v_rcp_f32_e32 v165, v165
	v_rcp_f32_e32 v166, v166
	v_rcp_f32_e32 v167, v167
	v_rcp_f32_e32 v168, v168
	v_rcp_f32_e32 v169, v169
	v_mul_f32_e32 v24, v24, v154
	v_mul_f32_e32 v25, v25, v155
	v_mul_f32_e32 v26, v26, v156
	v_mul_f32_e32 v27, v27, v157
	v_mul_f32_e32 v16, v16, v158
	v_mul_f32_e32 v17, v17, v159
	v_mul_f32_e32 v18, v18, v160
	v_mul_f32_e32 v19, v19, v161
	v_cvt_pk_bf16_f32 v154, v24, v25
	v_cvt_pk_bf16_f32 v155, v26, v27
	v_cvt_pk_bf16_f32 v156, v16, v17
	v_cvt_pk_bf16_f32 v157, v18, v19
	global_store_dwordx4 v[178:179], v[154:157], off
	v_lshl_add_u64 v[178:179], v[178:179], 0, s[98:99]
	s_nop 1
	v_mul_f32_e32 v8, v8, v162
	v_mul_f32_e32 v9, v9, v163
	v_mul_f32_e32 v10, v10, v164
	v_mul_f32_e32 v11, v11, v165
	v_mul_f32_e32 v0, v0, v166
	v_mul_f32_e32 v1, v1, v167
	v_mul_f32_e32 v2, v2, v168
	v_mul_f32_e32 v3, v3, v169
	v_cvt_pk_bf16_f32 v162, v8, v9
	v_cvt_pk_bf16_f32 v163, v10, v11
	v_cvt_pk_bf16_f32 v164, v0, v1
	v_cvt_pk_bf16_f32 v165, v2, v3
	global_store_dwordx4 v[178:179], v[162:165], off
	s_andn2_b64 vcc, exec, s[4:5]
	s_mov_b64 s[4:5], -1
	s_cbranch_vccnz .LBB0_220
	s_andn2_b64 vcc, exec, s[0:1]
	s_cbranch_vccnz .LBB0_219
	s_barrier
	s_branch .LBB0_219

; #define LAS __attribute__((address_space(3)))
; __device__ __forceinline__ unsigned cvt_pk2(float lo, float hi) { f32x2c v = {lo, hi}; bf16x2c q = __builtin_convertvector(v, bf16x2c); return __builtin_bit_cast(unsigned, q); }
;     __device__ __forceinline__ void operator()(const f32x4 (&acc)[2][2][4][2], const pg8::Unit& u, int wr, int wc, int fr, int fq) const {
;         const int row0 = u.pm * 256 + wr * 64 + fr, col0 = u.pn * 128 + wc * 32 + 8 * fq;
;         const LAS float* rt = rt_.of(u.pm) + wr * 64 + fr;
; #pragma unroll
;         for (int ai = 0; ai < 2; ++ai)
; #pragma unroll
;             for (int m = 0; m < 4; ++m) { bf16_t* rowp = O + (size_t)(row0 + ai * 128 + m * 16) * FF + col0; const float r = rt[ai * 128 + m * 16];
;                 const float rl = -r * LOG2E, r2 = r * r; unsigned w[4];
; #pragma unroll
;                 for (int n = 0; n < 2; ++n)
; #pragma unroll
;                     for (int h = 0; h < 2; ++h) { const f32x2v g = {acc[ai][0][m][n][2 * h], acc[ai][0][m][n][2 * h + 1]}, uu = {acc[ai][1][m][n][2 * h], acc[ai][1][m][n][2 * h + 1]};
;                         const f32x2v t = g * rl; f32x2v d = {__builtin_amdgcn_exp2f(t.x), __builtin_amdgcn_exp2f(t.y)}; d = d + 1.0f;
;                         const f32x2v q = {__builtin_amdgcn_rcpf(d.x), __builtin_amdgcn_rcpf(d.y)}; const f32x2v o = ((g * uu) * r2) * q;
;                         w[2 * n + h] = cvt_pk2(o.x, o.y); }
;                 u32x4 wv; wv.x = w[0]; wv.y = w[1]; wv.z = w[2]; wv.w = w[3];
;                 *(u32x4*)rowp = wv; }
.LBB0_813:
	s_cmp_eq_u32 s34, s48
	s_cselect_b32 s13, s62, 0x300
	s_cmp_lg_u32 s34, s49
	s_cselect_b32 s13, s13, 0x100
	s_cmp_lg_u32 s34, s47
	s_cselect_b32 s13, s13, 0
	v_lshl_add_u32 v154, s13, 2, v148
	ds_read2_b32 v[200:201], v154 offset1:16
	ds_read2_b32 v[202:203], v154 offset0:32 offset1:48
	ds_read2_b32 v[204:205], v154 offset0:128 offset1:144
	ds_read2_b32 v[206:207], v154 offset0:160 offset1:176
	v_lshl_add_u32 v153, s34, 8, v146
	v_lshl_or_b32 v158, s64, 7, v149
	v_mov_b64_e32 v[178:179], s[40:41]
	s_mov_b32 s98, 0x1600
	v_lshlrev_b32_e32 v158, 1, v158
	v_mov_b32_e32 v159, 0
	v_mad_i64_i32 v[178:179], s[20:21], v153, s98, v[178:179]
	s_mov_b32 s98, 0x16000
	s_mov_b32 s99, 0
	s_mov_b32 s100, 0x6e000
	s_mov_b32 s101, 0
	v_lshl_add_u64 v[178:179], v[178:179], 0, v[158:159]
	s_waitcnt lgkmcnt(0)
	v_mul_f32_e32 v208, 0xbfb8aa3b, v200
	v_mul_f32_e32 v228, v200, v200
	v_mul_f32_e32 v210, 0xbfb8aa3b, v201
	v_mul_f32_e32 v230, v201, v201
	v_mul_f32_e32 v212, 0xbfb8aa3b, v202
	v_mul_f32_e32 v232, v202, v202
	v_mul_f32_e32 v214, 0xbfb8aa3b, v203
	v_mul_f32_e32 v234, v203, v203
	v_mul_f32_e32 v216, 0xbfb8aa3b, v204
	v_mul_f32_e32 v236, v204, v204
	v_mul_f32_e32 v218, 0xbfb8aa3b, v205
	v_mul_f32_e32 v238, v205, v205
	v_mul_f32_e32 v220, 0xbfb8aa3b, v206
	v_mul_f32_e32 v240, v206, v206
	v_mul_f32_e32 v222, 0xbfb8aa3b, v207
	v_mul_f32_e32 v242, v207, v207
	v_rcp_f32_e32 v228, v228
	v_rcp_f32_e32 v230, v230
	v_rcp_f32_e32 v232, v232
	v_rcp_f32_e32 v234, v234
	v_rcp_f32_e32 v236, v236
	v_rcp_f32_e32 v238, v238
	v_rcp_f32_e32 v240, v240
	v_rcp_f32_e32 v242, v242
	v_mul_f32_e32 v154, v124, v208
	v_mul_f32_e32 v155, v125, v208
	v_mul_f32_e32 v156, v126, v208
	v_mul_f32_e32 v157, v127, v208
	v_mul_f32_e32 v158, v116, v208
	v_mul_f32_e32 v159, v117, v208
	v_mul_f32_e32 v160, v118, v208
	v_mul_f32_e32 v161, v119, v208
	v_exp_f32_e32 v154, v154
	v_exp_f32_e32 v155, v155
	v_exp_f32_e32 v156, v156
	v_exp_f32_e32 v157, v157
	v_exp_f32_e32 v158, v158
	v_exp_f32_e32 v159, v159
	v_exp_f32_e32 v160, v160
	v_exp_f32_e32 v161, v161
	v_mul_f32_e32 v162, v108, v210
	v_mul_f32_e32 v163, v109, v210
	v_mul_f32_e32 v164, v110, v210
	v_mul_f32_e32 v165, v111, v210
	v_mul_f32_e32 v166, v100, v210
	v_mul_f32_e32 v167, v101, v210
	v_mul_f32_e32 v168, v102, v210
	v_mul_f32_e32 v169, v103, v210
	v_exp_f32_e32 v162, v162
	v_exp_f32_e32 v163, v163
	v_exp_f32_e32 v164, v164
	v_exp_f32_e32 v165, v165
	v_exp_f32_e32 v166, v166
	v_exp_f32_e32 v167, v167
	v_exp_f32_e32 v168, v168
	v_exp_f32_e32 v169, v169
	v_mul_f32_e32 v120, v124, v120
	v_mul_f32_e32 v121, v125, v121
	v_mul_f32_e32 v122, v126, v122
	v_mul_f32_e32 v123, v127, v123
	v_mul_f32_e32 v112, v116, v112
	v_mul_f32_e32 v113, v117, v113
	v_mul_f32_e32 v114, v118, v114
	v_mul_f32_e32 v115, v119, v115
	v_fma_f32 v154, v154, v228, v228
	v_fma_f32 v155, v155, v228, v228
	v_fma_f32 v156, v156, v228, v228
	v_fma_f32 v157, v157, v228, v228
	v_fma_f32 v158, v158, v228, v228
	v_fma_f32 v159, v159, v228, v228
	v_fma_f32 v160, v160, v228, v228
	v_fma_f32 v161, v161, v228, v228
	v_rcp_f32_e32 v154, v154
	v_rcp_f32_e32 v155, v155
	v_rcp_f32_e32 v156, v156
	v_rcp_f32_e32 v157, v157
	v_rcp_f32_e32 v158, v158
	v_rcp_f32_e32 v159, v159
	v_rcp_f32_e32 v160, v160
	v_rcp_f32_e32 v161, v161
	v_mul_f32_e32 v170, v92, v212
	v_mul_f32_e32 v171, v93, v212
	v_mul_f32_e32 v172, v94, v212
	v_mul_f32_e32 v173, v95, v212
	v_mul_f32_e32 v174, v84, v212
	v_mul_f32_e32 v175, v85, v212
	v_mul_f32_e32 v176, v86, v212
	v_mul_f32_e32 v177, v87, v212
	v_exp_f32_e32 v170, v170
	v_exp_f32_e32 v171, v171
	v_exp_f32_e32 v172, v172
	v_exp_f32_e32 v173, v173
	v_exp_f32_e32 v174, v174
	v_exp_f32_e32 v175, v175
	v_exp_f32_e32 v176, v176
	v_exp_f32_e32 v177, v177
	v_mul_f32_e32 v104, v108, v104
	v_mul_f32_e32 v105, v109, v105
	v_mul_f32_e32 v106, v110, v106
	v_mul_f32_e32 v107, v111, v107
	v_mul_f32_e32 v96, v100, v96
	v_mul_f32_e32 v97, v101, v97
	v_mul_f32_e32 v98, v102, v98
	v_mul_f32_e32 v99, v103, v99
	v_fma_f32 v162, v162, v230, v230
	v_fma_f32 v163, v163, v230, v230
	v_fma_f32 v164, v164, v230, v230
	v_fma_f32 v165, v165, v230, v230
	v_fma_f32 v166, v166, v230, v230
	v_fma_f32 v167, v167, v230, v230
	v_fma_f32 v168, v168, v230, v230
	v_fma_f32 v169, v169, v230, v230
	v_rcp_f32_e32 v162, v162
	v_rcp_f32_e32 v163, v163
	v_rcp_f32_e32 v164, v164
	v_rcp_f32_e32 v165, v165
	v_rcp_f32_e32 v166, v166
	v_rcp_f32_e32 v167, v167
	v_rcp_f32_e32 v168, v168
	v_rcp_f32_e32 v169, v169
	v_mul_f32_e32 v120, v120, v154
	v_mul_f32_e32 v121, v121, v155
	v_mul_f32_e32 v122, v122, v156
	v_mul_f32_e32 v123, v123, v157
	v_mul_f32_e32 v112, v112, v158
	v_mul_f32_e32 v113, v113, v159
	v_mul_f32_e32 v114, v114, v160
	v_mul_f32_e32 v115, v115, v161
	v_cvt_pk_bf16_f32 v154, v120, v121
	v_cvt_pk_bf16_f32 v155, v122, v123
	v_cvt_pk_bf16_f32 v156, v112, v113
	v_cvt_pk_bf16_f32 v157, v114, v115
	global_store_dwordx4 v[178:179], v[154:157], off
	v_lshl_add_u64 v[178:179], v[178:179], 0, s[98:99]
	s_nop 1
	v_mul_f32_e32 v154, v76, v214
	v_mul_f32_e32 v155, v77, v214
	v_mul_f32_e32 v156, v78, v214
	v_mul_f32_e32 v157, v79, v214
	v_mul_f32_e32 v158, v68, v214
	v_mul_f32_e32 v159, v69, v214
	v_mul_f32_e32 v160, v70, v214
	v_mul_f32_e32 v161, v71, v214
	v_exp_f32_e32 v154, v154
	v_exp_f32_e32 v155, v155
	v_exp_f32_e32 v156, v156
	v_exp_f32_e32 v157, v157
	v_exp_f32_e32 v158, v158
	v_exp_f32_e32 v159, v159
	v_exp_f32_e32 v160, v160
	v_exp_f32_e32 v161, v161
	v_mul_f32_e32 v88, v92, v88
	v_mul_f32_e32 v89, v93, v89
	v_mul_f32_e32 v90, v94, v90
	v_mul_f32_e32 v91, v95, v91
	v_mul_f32_e32 v80, v84, v80
	v_mul_f32_e32 v81, v85, v81
	v_mul_f32_e32 v82, v86, v82
	v_mul_f32_e32 v83, v87, v83
; __device__ __forceinline__ unsigned cvt_pk2(float lo, float hi) { f32x2c v = {lo, hi}; bf16x2c q = __builtin_convertvector(v, bf16x2c); return __builtin_bit_cast(unsigned, q); }
;     __device__ __forceinline__ void operator()(const f32x4 (&acc)[2][2][4][2], const pg8::Unit& u, int wr, int wc, int fr, int fq) const {
;     ...
;             for (int m = 0; m < 4; ++m) { bf16_t* rowp = O + (size_t)(row0 + ai * 128 + m * 16) * FF + col0; const float r = rt[ai * 128 + m * 16];
;                 const float rl = -r * LOG2E, r2 = r * r; unsigned w[4];
; #pragma unroll
;                 for (int n = 0; n < 2; ++n)
; #pragma unroll
;                     for (int h = 0; h < 2; ++h) { const f32x2v g = {acc[ai][0][m][n][2 * h], acc[ai][0][m][n][2 * h + 1]}, uu = {acc[ai][1][m][n][2 * h], acc[ai][1][m][n][2 * h + 1]};
;                         const f32x2v t = g * rl; f32x2v d = {__builtin_amdgcn_exp2f(t.x), __builtin_amdgcn_exp2f(t.y)}; d = d + 1.0f;
;                         const f32x2v q = {__builtin_amdgcn_rcpf(d.x), __builtin_amdgcn_rcpf(d.y)}; const f32x2v o = ((g * uu) * r2) * q;
;                         w[2 * n + h] = cvt_pk2(o.x, o.y); }
;                 u32x4 wv; wv.x = w[0]; wv.y = w[1]; wv.z = w[2]; wv.w = w[3];
;                 *(u32x4*)rowp = wv; }
	v_fma_f32 v170, v170, v232, v232
	v_fma_f32 v171, v171, v232, v232
	v_fma_f32 v172, v172, v232, v232
	v_fma_f32 v173, v173, v232, v232
	v_fma_f32 v174, v174, v232, v232
	v_fma_f32 v175, v175, v232, v232
	v_fma_f32 v176, v176, v232, v232
	v_fma_f32 v177, v177, v232, v232
	v_rcp_f32_e32 v170, v170
	v_rcp_f32_e32 v171, v171
	v_rcp_f32_e32 v172, v172
	v_rcp_f32_e32 v173, v173
	v_rcp_f32_e32 v174, v174
	v_rcp_f32_e32 v175, v175
	v_rcp_f32_e32 v176, v176
	v_rcp_f32_e32 v177, v177
	v_mul_f32_e32 v104, v104, v162
	v_mul_f32_e32 v105, v105, v163
	v_mul_f32_e32 v106, v106, v164
	v_mul_f32_e32 v107, v107, v165
	v_mul_f32_e32 v96, v96, v166
	v_mul_f32_e32 v97, v97, v167
	v_mul_f32_e32 v98, v98, v168
	v_mul_f32_e32 v99, v99, v169
	v_cvt_pk_bf16_f32 v162, v104, v105
	v_cvt_pk_bf16_f32 v163, v106, v107
	v_cvt_pk_bf16_f32 v164, v96, v97
	v_cvt_pk_bf16_f32 v165, v98, v99
	global_store_dwordx4 v[178:179], v[162:165], off
	v_lshl_add_u64 v[178:179], v[178:179], 0, s[98:99]
	s_nop 1
	v_mul_f32_e32 v162, v60, v216
	v_mul_f32_e32 v163, v61, v216
	v_mul_f32_e32 v164, v62, v216
	v_mul_f32_e32 v165, v63, v216
	v_mul_f32_e32 v166, v52, v216
	v_mul_f32_e32 v167, v53, v216
	v_mul_f32_e32 v168, v54, v216
	v_mul_f32_e32 v169, v55, v216
	v_exp_f32_e32 v162, v162
	v_exp_f32_e32 v163, v163
	v_exp_f32_e32 v164, v164
	v_exp_f32_e32 v165, v165
	v_exp_f32_e32 v166, v166
	v_exp_f32_e32 v167, v167
	v_exp_f32_e32 v168, v168
	v_exp_f32_e32 v169, v169
	v_mul_f32_e32 v72, v76, v72
	v_mul_f32_e32 v73, v77, v73
	v_mul_f32_e32 v74, v78, v74
	v_mul_f32_e32 v75, v79, v75
	v_mul_f32_e32 v64, v68, v64
	v_mul_f32_e32 v65, v69, v65
	v_mul_f32_e32 v66, v70, v66
	v_mul_f32_e32 v67, v71, v67
	v_fma_f32 v154, v154, v234, v234
	v_fma_f32 v155, v155, v234, v234
	v_fma_f32 v156, v156, v234, v234
	v_fma_f32 v157, v157, v234, v234
	v_fma_f32 v158, v158, v234, v234
	v_fma_f32 v159, v159, v234, v234
	v_fma_f32 v160, v160, v234, v234
	v_fma_f32 v161, v161, v234, v234
	v_rcp_f32_e32 v154, v154
	v_rcp_f32_e32 v155, v155
	v_rcp_f32_e32 v156, v156
	v_rcp_f32_e32 v157, v157
	v_rcp_f32_e32 v158, v158
	v_rcp_f32_e32 v159, v159
	v_rcp_f32_e32 v160, v160
	v_rcp_f32_e32 v161, v161
	v_mul_f32_e32 v88, v88, v170
	v_mul_f32_e32 v89, v89, v171
	v_mul_f32_e32 v90, v90, v172
	v_mul_f32_e32 v91, v91, v173
	v_mul_f32_e32 v80, v80, v174
	v_mul_f32_e32 v81, v81, v175
	v_mul_f32_e32 v82, v82, v176
	v_mul_f32_e32 v83, v83, v177
	v_cvt_pk_bf16_f32 v170, v88, v89
	v_cvt_pk_bf16_f32 v171, v90, v91
	v_cvt_pk_bf16_f32 v172, v80, v81
	v_cvt_pk_bf16_f32 v173, v82, v83
	global_store_dwordx4 v[178:179], v[170:173], off
	v_lshl_add_u64 v[178:179], v[178:179], 0, s[98:99]
	s_nop 1
	v_mul_f32_e32 v170, v44, v218
	v_mul_f32_e32 v171, v45, v218
	v_mul_f32_e32 v172, v46, v218
	v_mul_f32_e32 v173, v47, v218
	v_mul_f32_e32 v174, v36, v218
	v_mul_f32_e32 v175, v37, v218
	v_mul_f32_e32 v176, v38, v218
	v_mul_f32_e32 v177, v39, v218
	v_exp_f32_e32 v170, v170
	v_exp_f32_e32 v171, v171
	v_exp_f32_e32 v172, v172
	v_exp_f32_e32 v173, v173
	v_exp_f32_e32 v174, v174
	v_exp_f32_e32 v175, v175
	v_exp_f32_e32 v176, v176
	v_exp_f32_e32 v177, v177
	v_mul_f32_e32 v56, v60, v56
	v_mul_f32_e32 v57, v61, v57
	v_mul_f32_e32 v58, v62, v58
	v_mul_f32_e32 v59, v63, v59
	v_mul_f32_e32 v48, v52, v48
	v_mul_f32_e32 v49, v53, v49
	v_mul_f32_e32 v50, v54, v50
	v_mul_f32_e32 v51, v55, v51
	v_fma_f32 v162, v162, v236, v236
	v_fma_f32 v163, v163, v236, v236
	v_fma_f32 v164, v164, v236, v236
	v_fma_f32 v165, v165, v236, v236
	v_fma_f32 v166, v166, v236, v236
	v_fma_f32 v167, v167, v236, v236
	v_fma_f32 v168, v168, v236, v236
	v_fma_f32 v169, v169, v236, v236
	v_rcp_f32_e32 v162, v162
	v_rcp_f32_e32 v163, v163
	v_rcp_f32_e32 v164, v164
	v_rcp_f32_e32 v165, v165
	v_rcp_f32_e32 v166, v166
	v_rcp_f32_e32 v167, v167
	v_rcp_f32_e32 v168, v168
	v_rcp_f32_e32 v169, v169
	v_mul_f32_e32 v72, v72, v154
	v_mul_f32_e32 v73, v73, v155
	v_mul_f32_e32 v74, v74, v156
	v_mul_f32_e32 v75, v75, v157
	v_mul_f32_e32 v64, v64, v158
	v_mul_f32_e32 v65, v65, v159
	v_mul_f32_e32 v66, v66, v160
	v_mul_f32_e32 v67, v67, v161
	v_cvt_pk_bf16_f32 v154, v72, v73
	v_cvt_pk_bf16_f32 v155, v74, v75
	v_cvt_pk_bf16_f32 v156, v64, v65
	v_cvt_pk_bf16_f32 v157, v66, v67
	global_store_dwordx4 v[178:179], v[154:157], off
	v_lshl_add_u64 v[178:179], v[178:179], 0, s[100:101]
	s_nop 1
	v_mul_f32_e32 v154, v28, v220
	v_mul_f32_e32 v155, v29, v220
	v_mul_f32_e32 v156, v30, v220
	v_mul_f32_e32 v157, v31, v220
	v_mul_f32_e32 v158, v20, v220
	v_mul_f32_e32 v159, v21, v220
	v_mul_f32_e32 v160, v22, v220
	v_mul_f32_e32 v161, v23, v220
	v_exp_f32_e32 v154, v154
	v_exp_f32_e32 v155, v155
	v_exp_f32_e32 v156, v156
	v_exp_f32_e32 v157, v157
	v_exp_f32_e32 v158, v158
; #define PG8_BAR __builtin_amdgcn_s_barrier()
; __device__ __forceinline__ unsigned cvt_pk2(float lo, float hi) { f32x2c v = {lo, hi}; bf16x2c q = __builtin_convertvector(v, bf16x2c); return __builtin_bit_cast(unsigned, q); }
; template <class Epi, class Sched, bool ALIGN_EPI = false, bool SP2 = false>
; __device__ __forceinline__ void gemm_phase(PG8_LAS unsigned char* lds, const Gemm g, const Sched& S, const Epi& E) {
;     ...
;         if (!has_next) break;
; #pragma unroll
;         for (int a = 0; a < 2; ++a)
; #pragma unroll
;             for (int b = 0; b < 2; ++b)
; #pragma unroll
;                 for (int m = 0; m < 4; ++m)
; #pragma unroll
;                     for (int n = 0; n < 2; ++n) acc[a][b][m][n] = (f32x4){0.f, 0.f, 0.f, 0.f};
;         cur = nxt; cA = nA; cB = nB; ++ui;
;         if constexpr (ALIGN_EPI) { if (wr == 1) PG8_BAR; }
;     __device__ __forceinline__ void operator()(const f32x4 (&acc)[2][2][4][2], const pg8::Unit& u, int wr, int wc, int fr, int fq) const {
;     ...
;             for (int m = 0; m < 4; ++m) { bf16_t* rowp = O + (size_t)(row0 + ai * 128 + m * 16) * FF + col0; const float r = rt[ai * 128 + m * 16];
;                 const float rl = -r * LOG2E, r2 = r * r; unsigned w[4];
; #pragma unroll
;                 for (int n = 0; n < 2; ++n)
; #pragma unroll
;                     for (int h = 0; h < 2; ++h) { const f32x2v g = {acc[ai][0][m][n][2 * h], acc[ai][0][m][n][2 * h + 1]}, uu = {acc[ai][1][m][n][2 * h], acc[ai][1][m][n][2 * h + 1]};
;                         const f32x2v t = g * rl; f32x2v d = {__builtin_amdgcn_exp2f(t.x), __builtin_amdgcn_exp2f(t.y)}; d = d + 1.0f;
;                         const f32x2v q = {__builtin_amdgcn_rcpf(d.x), __builtin_amdgcn_rcpf(d.y)}; const f32x2v o = ((g * uu) * r2) * q;
;                         w[2 * n + h] = cvt_pk2(o.x, o.y); }
;                 u32x4 wv; wv.x = w[0]; wv.y = w[1]; wv.z = w[2]; wv.w = w[3];
;                 *(u32x4*)rowp = wv; }
	v_exp_f32_e32 v159, v159
	v_exp_f32_e32 v160, v160
	v_exp_f32_e32 v161, v161
	v_mul_f32_e32 v40, v44, v40
	v_mul_f32_e32 v41, v45, v41
	v_mul_f32_e32 v42, v46, v42
	v_mul_f32_e32 v43, v47, v43
	v_mul_f32_e32 v32, v36, v32
	v_mul_f32_e32 v33, v37, v33
	v_mul_f32_e32 v34, v38, v34
	v_mul_f32_e32 v35, v39, v35
	v_fma_f32 v170, v170, v238, v238
	v_fma_f32 v171, v171, v238, v238
	v_fma_f32 v172, v172, v238, v238
	v_fma_f32 v173, v173, v238, v238
	v_fma_f32 v174, v174, v238, v238
	v_fma_f32 v175, v175, v238, v238
	v_fma_f32 v176, v176, v238, v238
	v_fma_f32 v177, v177, v238, v238
	v_rcp_f32_e32 v170, v170
	v_rcp_f32_e32 v171, v171
	v_rcp_f32_e32 v172, v172
	v_rcp_f32_e32 v173, v173
	v_rcp_f32_e32 v174, v174
	v_rcp_f32_e32 v175, v175
	v_rcp_f32_e32 v176, v176
	v_rcp_f32_e32 v177, v177
	v_mul_f32_e32 v56, v56, v162
	v_mul_f32_e32 v57, v57, v163
	v_mul_f32_e32 v58, v58, v164
	v_mul_f32_e32 v59, v59, v165
	v_mul_f32_e32 v48, v48, v166
	v_mul_f32_e32 v49, v49, v167
	v_mul_f32_e32 v50, v50, v168
	v_mul_f32_e32 v51, v51, v169
	v_cvt_pk_bf16_f32 v162, v56, v57
	v_cvt_pk_bf16_f32 v163, v58, v59
	v_cvt_pk_bf16_f32 v164, v48, v49
	v_cvt_pk_bf16_f32 v165, v50, v51
	global_store_dwordx4 v[178:179], v[162:165], off
	v_lshl_add_u64 v[178:179], v[178:179], 0, s[98:99]
	s_nop 1
	v_mul_f32_e32 v162, v12, v222
	v_mul_f32_e32 v163, v13, v222
	v_mul_f32_e32 v164, v14, v222
	v_mul_f32_e32 v165, v15, v222
	v_mul_f32_e32 v166, v4, v222
	v_mul_f32_e32 v167, v5, v222
	v_mul_f32_e32 v168, v6, v222
	v_mul_f32_e32 v169, v7, v222
	v_exp_f32_e32 v162, v162
	v_exp_f32_e32 v163, v163
	v_exp_f32_e32 v164, v164
	v_exp_f32_e32 v165, v165
	v_exp_f32_e32 v166, v166
	v_exp_f32_e32 v167, v167
	v_exp_f32_e32 v168, v168
	v_exp_f32_e32 v169, v169
	v_mul_f32_e32 v24, v28, v24
	v_mul_f32_e32 v25, v29, v25
	v_mul_f32_e32 v26, v30, v26
	v_mul_f32_e32 v27, v31, v27
	v_mul_f32_e32 v16, v20, v16
	v_mul_f32_e32 v17, v21, v17
	v_mul_f32_e32 v18, v22, v18
	v_mul_f32_e32 v19, v23, v19
	v_fma_f32 v154, v154, v240, v240
	v_fma_f32 v155, v155, v240, v240
	v_fma_f32 v156, v156, v240, v240
	v_fma_f32 v157, v157, v240, v240
	v_fma_f32 v158, v158, v240, v240
	v_fma_f32 v159, v159, v240, v240
	v_fma_f32 v160, v160, v240, v240
	v_fma_f32 v161, v161, v240, v240
	v_rcp_f32_e32 v154, v154
	v_rcp_f32_e32 v155, v155
	v_rcp_f32_e32 v156, v156
	v_rcp_f32_e32 v157, v157
	v_rcp_f32_e32 v158, v158
	v_rcp_f32_e32 v159, v159
	v_rcp_f32_e32 v160, v160
	v_rcp_f32_e32 v161, v161
	v_mul_f32_e32 v40, v40, v170
	v_mul_f32_e32 v41, v41, v171
	v_mul_f32_e32 v42, v42, v172
	v_mul_f32_e32 v43, v43, v173
	v_mul_f32_e32 v32, v32, v174
	v_mul_f32_e32 v33, v33, v175
	v_mul_f32_e32 v34, v34, v176
	v_mul_f32_e32 v35, v35, v177
	v_cvt_pk_bf16_f32 v170, v40, v41
	v_cvt_pk_bf16_f32 v171, v42, v43
	v_cvt_pk_bf16_f32 v172, v32, v33
	v_cvt_pk_bf16_f32 v173, v34, v35
	global_store_dwordx4 v[178:179], v[170:173], off
	v_lshl_add_u64 v[178:179], v[178:179], 0, s[98:99]
	s_nop 1
	v_mul_f32_e32 v8, v12, v8
	v_mul_f32_e32 v9, v13, v9
	v_mul_f32_e32 v10, v14, v10
	v_mul_f32_e32 v11, v15, v11
	v_mul_f32_e32 v0, v4, v0
	v_mul_f32_e32 v1, v5, v1
	v_mul_f32_e32 v2, v6, v2
	v_mul_f32_e32 v3, v7, v3
	v_fma_f32 v162, v162, v242, v242
	v_fma_f32 v163, v163, v242, v242
	v_fma_f32 v164, v164, v242, v242
	v_fma_f32 v165, v165, v242, v242
	v_fma_f32 v166, v166, v242, v242
	v_fma_f32 v167, v167, v242, v242
	v_fma_f32 v168, v168, v242, v242
	v_fma_f32 v169, v169, v242, v242
	v_rcp_f32_e32 v162, v162
	v_rcp_f32_e32 v163, v163
	v_rcp_f32_e32 v164, v164
	v_rcp_f32_e32 v165, v165
	v_rcp_f32_e32 v166, v166
	v_rcp_f32_e32 v167, v167
	v_rcp_f32_e32 v168, v168
	v_rcp_f32_e32 v169, v169
	v_mul_f32_e32 v24, v24, v154
	v_mul_f32_e32 v25, v25, v155
	v_mul_f32_e32 v26, v26, v156
	v_mul_f32_e32 v27, v27, v157
	v_mul_f32_e32 v16, v16, v158
	v_mul_f32_e32 v17, v17, v159
	v_mul_f32_e32 v18, v18, v160
	v_mul_f32_e32 v19, v19, v161
	v_cvt_pk_bf16_f32 v154, v24, v25
	v_cvt_pk_bf16_f32 v155, v26, v27
	v_cvt_pk_bf16_f32 v156, v16, v17
	v_cvt_pk_bf16_f32 v157, v18, v19
	global_store_dwordx4 v[178:179], v[154:157], off
	v_lshl_add_u64 v[178:179], v[178:179], 0, s[98:99]
	s_nop 1
	v_mul_f32_e32 v8, v8, v162
	v_mul_f32_e32 v9, v9, v163
	v_mul_f32_e32 v10, v10, v164
	v_mul_f32_e32 v11, v11, v165
	v_mul_f32_e32 v0, v0, v166
	v_mul_f32_e32 v1, v1, v167
	v_mul_f32_e32 v2, v2, v168
	v_mul_f32_e32 v3, v3, v169
	v_cvt_pk_bf16_f32 v162, v8, v9
	v_cvt_pk_bf16_f32 v163, v10, v11
	v_cvt_pk_bf16_f32 v164, v0, v1
	v_cvt_pk_bf16_f32 v165, v2, v3
	global_store_dwordx4 v[178:179], v[162:165], off
	s_andn2_b64 vcc, exec, s[4:5]
	s_mov_b64 s[4:5], -1
	s_cbranch_vccnz .LBB0_806
	s_andn2_b64 vcc, exec, s[0:1]
	s_cbranch_vccnz .LBB0_805
	s_barrier
	s_branch .LBB0_805

; #define LAS __attribute__((address_space(3)))
; __device__ __forceinline__ unsigned cvt_pk2(float lo, float hi) { f32x2c v = {lo, hi}; bf16x2c q = __builtin_convertvector(v, bf16x2c); return __builtin_bit_cast(unsigned, q); }
;     __device__ __forceinline__ void operator()(const f32x4 (&acc)[2][2][4][2], const pg8::Unit& u, int wr, int wc, int fr, int fq) const {
;         const int row0 = u.pm * 256 + wr * 64 + fr, col0 = u.pn * 128 + wc * 32 + 8 * fq;
;         const LAS float* rt = rt_.of(u.pm) + wr * 64 + fr;
; #pragma unroll
;         for (int ai = 0; ai < 2; ++ai)
; #pragma unroll
;             for (int m = 0; m < 4; ++m) { bf16_t* rowp = O + (size_t)(row0 + ai * 128 + m * 16) * FF + col0; const float r = rt[ai * 128 + m * 16];
;                 const float rl = -r * LOG2E, r2 = r * r; unsigned w[4];
; #pragma unroll
;                 for (int n = 0; n < 2; ++n)
; #pragma unroll
;                     for (int h = 0; h < 2; ++h) { const f32x2v g = {acc[ai][0][m][n][2 * h], acc[ai][0][m][n][2 * h + 1]}, uu = {acc[ai][1][m][n][2 * h], acc[ai][1][m][n][2 * h + 1]};
;                         const f32x2v t = g * rl; f32x2v d = {__builtin_amdgcn_exp2f(t.x), __builtin_amdgcn_exp2f(t.y)}; d = d + 1.0f;
;                         const f32x2v q = {__builtin_amdgcn_rcpf(d.x), __builtin_amdgcn_rcpf(d.y)}; const f32x2v o = ((g * uu) * r2) * q;
;                         w[2 * n + h] = cvt_pk2(o.x, o.y); }
;                 u32x4 wv; wv.x = w[0]; wv.y = w[1]; wv.z = w[2]; wv.w = w[3];
;                 *(u32x4*)rowp = wv; }
.LBB0_1743:
	s_cmp_eq_u32 s34, s45
	s_cselect_b32 s13, s60, 0x300
	s_cmp_lg_u32 s34, s46
	s_cselect_b32 s13, s13, 0x100
	s_cmp_lg_u32 s34, s47
	s_cselect_b32 s13, s13, 0
	v_lshl_add_u32 v154, s13, 2, v148
	ds_read2_b32 v[200:201], v154 offset1:16
	ds_read2_b32 v[202:203], v154 offset0:32 offset1:48
	ds_read2_b32 v[204:205], v154 offset0:128 offset1:144
	ds_read2_b32 v[206:207], v154 offset0:160 offset1:176
	v_lshl_add_u32 v153, s34, 8, v146
	v_lshl_or_b32 v158, s62, 7, v149
	v_mov_b64_e32 v[178:179], s[40:41]
	s_mov_b32 s98, 0x1600
	v_lshlrev_b32_e32 v158, 1, v158
	v_mov_b32_e32 v159, 0
	v_mad_i64_i32 v[178:179], s[20:21], v153, s98, v[178:179]
	s_mov_b32 s98, 0x16000
	s_mov_b32 s99, 0
	s_mov_b32 s100, 0x6e000
	s_mov_b32 s101, 0
	v_lshl_add_u64 v[178:179], v[178:179], 0, v[158:159]
	s_waitcnt lgkmcnt(0)
	v_mul_f32_e32 v208, 0xbfb8aa3b, v200
	v_mul_f32_e32 v228, v200, v200
	v_mul_f32_e32 v210, 0xbfb8aa3b, v201
	v_mul_f32_e32 v230, v201, v201
	v_mul_f32_e32 v212, 0xbfb8aa3b, v202
	v_mul_f32_e32 v232, v202, v202
	v_mul_f32_e32 v214, 0xbfb8aa3b, v203
	v_mul_f32_e32 v234, v203, v203
	v_mul_f32_e32 v216, 0xbfb8aa3b, v204
	v_mul_f32_e32 v236, v204, v204
	v_mul_f32_e32 v218, 0xbfb8aa3b, v205
	v_mul_f32_e32 v238, v205, v205
	v_mul_f32_e32 v220, 0xbfb8aa3b, v206
	v_mul_f32_e32 v240, v206, v206
	v_mul_f32_e32 v222, 0xbfb8aa3b, v207
	v_mul_f32_e32 v242, v207, v207
	v_rcp_f32_e32 v228, v228
	v_rcp_f32_e32 v230, v230
	v_rcp_f32_e32 v232, v232
	v_rcp_f32_e32 v234, v234
	v_rcp_f32_e32 v236, v236
	v_rcp_f32_e32 v238, v238
	v_rcp_f32_e32 v240, v240
	v_rcp_f32_e32 v242, v242
	v_mul_f32_e32 v154, v124, v208
	v_mul_f32_e32 v155, v125, v208
	v_mul_f32_e32 v156, v126, v208
	v_mul_f32_e32 v157, v127, v208
	v_mul_f32_e32 v158, v116, v208
	v_mul_f32_e32 v159, v117, v208
	v_mul_f32_e32 v160, v118, v208
	v_mul_f32_e32 v161, v119, v208
	v_exp_f32_e32 v154, v154
	v_exp_f32_e32 v155, v155
	v_exp_f32_e32 v156, v156
	v_exp_f32_e32 v157, v157
	v_exp_f32_e32 v158, v158
	v_exp_f32_e32 v159, v159
	v_exp_f32_e32 v160, v160
	v_exp_f32_e32 v161, v161
	v_mul_f32_e32 v162, v108, v210
	v_mul_f32_e32 v163, v109, v210
	v_mul_f32_e32 v164, v110, v210
	v_mul_f32_e32 v165, v111, v210
	v_mul_f32_e32 v166, v100, v210
	v_mul_f32_e32 v167, v101, v210
	v_mul_f32_e32 v168, v102, v210
	v_mul_f32_e32 v169, v103, v210
	v_exp_f32_e32 v162, v162
	v_exp_f32_e32 v163, v163
	v_exp_f32_e32 v164, v164
	v_exp_f32_e32 v165, v165
	v_exp_f32_e32 v166, v166
	v_exp_f32_e32 v167, v167
	v_exp_f32_e32 v168, v168
	v_exp_f32_e32 v169, v169
	v_mul_f32_e32 v120, v124, v120
	v_mul_f32_e32 v121, v125, v121
	v_mul_f32_e32 v122, v126, v122
	v_mul_f32_e32 v123, v127, v123
	v_mul_f32_e32 v112, v116, v112
	v_mul_f32_e32 v113, v117, v113
	v_mul_f32_e32 v114, v118, v114
	v_mul_f32_e32 v115, v119, v115
	v_fma_f32 v154, v154, v228, v228
	v_fma_f32 v155, v155, v228, v228
	v_fma_f32 v156, v156, v228, v228
	v_fma_f32 v157, v157, v228, v228
	v_fma_f32 v158, v158, v228, v228
	v_fma_f32 v159, v159, v228, v228
	v_fma_f32 v160, v160, v228, v228
	v_fma_f32 v161, v161, v228, v228
	v_rcp_f32_e32 v154, v154
	v_rcp_f32_e32 v155, v155
	v_rcp_f32_e32 v156, v156
	v_rcp_f32_e32 v157, v157
	v_rcp_f32_e32 v158, v158
	v_rcp_f32_e32 v159, v159
	v_rcp_f32_e32 v160, v160
	v_rcp_f32_e32 v161, v161
	v_mul_f32_e32 v170, v92, v212
	v_mul_f32_e32 v171, v93, v212
	v_mul_f32_e32 v172, v94, v212
	v_mul_f32_e32 v173, v95, v212
	v_mul_f32_e32 v174, v84, v212
	v_mul_f32_e32 v175, v85, v212
	v_mul_f32_e32 v176, v86, v212
	v_mul_f32_e32 v177, v87, v212
	v_exp_f32_e32 v170, v170
	v_exp_f32_e32 v171, v171
	v_exp_f32_e32 v172, v172
	v_exp_f32_e32 v173, v173
	v_exp_f32_e32 v174, v174
	v_exp_f32_e32 v175, v175
	v_exp_f32_e32 v176, v176
	v_exp_f32_e32 v177, v177
	v_mul_f32_e32 v104, v108, v104
	v_mul_f32_e32 v105, v109, v105
	v_mul_f32_e32 v106, v110, v106
	v_mul_f32_e32 v107, v111, v107
	v_mul_f32_e32 v96, v100, v96
	v_mul_f32_e32 v97, v101, v97
	v_mul_f32_e32 v98, v102, v98
	v_mul_f32_e32 v99, v103, v99
	v_fma_f32 v162, v162, v230, v230
	v_fma_f32 v163, v163, v230, v230
	v_fma_f32 v164, v164, v230, v230
	v_fma_f32 v165, v165, v230, v230
	v_fma_f32 v166, v166, v230, v230
	v_fma_f32 v167, v167, v230, v230
	v_fma_f32 v168, v168, v230, v230
	v_fma_f32 v169, v169, v230, v230
	v_rcp_f32_e32 v162, v162
	v_rcp_f32_e32 v163, v163
	v_rcp_f32_e32 v164, v164
	v_rcp_f32_e32 v165, v165
	v_rcp_f32_e32 v166, v166
	v_rcp_f32_e32 v167, v167
	v_rcp_f32_e32 v168, v168
	v_rcp_f32_e32 v169, v169
	v_mul_f32_e32 v120, v120, v154
	v_mul_f32_e32 v121, v121, v155
	v_mul_f32_e32 v122, v122, v156
	v_mul_f32_e32 v123, v123, v157
	v_mul_f32_e32 v112, v112, v158
	v_mul_f32_e32 v113, v113, v159
	v_mul_f32_e32 v114, v114, v160
	v_mul_f32_e32 v115, v115, v161
	v_cvt_pk_bf16_f32 v154, v120, v121
	v_cvt_pk_bf16_f32 v155, v122, v123
	v_cvt_pk_bf16_f32 v156, v112, v113
	v_cvt_pk_bf16_f32 v157, v114, v115
	global_store_dwordx4 v[178:179], v[154:157], off
	v_lshl_add_u64 v[178:179], v[178:179], 0, s[98:99]
	s_nop 1
	v_mul_f32_e32 v154, v76, v214
	v_mul_f32_e32 v155, v77, v214
	v_mul_f32_e32 v156, v78, v214
	v_mul_f32_e32 v157, v79, v214
	v_mul_f32_e32 v158, v68, v214
	v_mul_f32_e32 v159, v69, v214
	v_mul_f32_e32 v160, v70, v214
	v_mul_f32_e32 v161, v71, v214
	v_exp_f32_e32 v154, v154
	v_exp_f32_e32 v155, v155
	v_exp_f32_e32 v156, v156
	v_exp_f32_e32 v157, v157
	v_exp_f32_e32 v158, v158
	v_exp_f32_e32 v159, v159
	v_exp_f32_e32 v160, v160
	v_exp_f32_e32 v161, v161
	v_mul_f32_e32 v88, v92, v88
	v_mul_f32_e32 v89, v93, v89
	v_mul_f32_e32 v90, v94, v90
	v_mul_f32_e32 v91, v95, v91
	v_mul_f32_e32 v80, v84, v80
	v_mul_f32_e32 v81, v85, v81
	v_mul_f32_e32 v82, v86, v82
	v_mul_f32_e32 v83, v87, v83
; __device__ __forceinline__ unsigned cvt_pk2(float lo, float hi) { f32x2c v = {lo, hi}; bf16x2c q = __builtin_convertvector(v, bf16x2c); return __builtin_bit_cast(unsigned, q); }
;     __device__ __forceinline__ void operator()(const f32x4 (&acc)[2][2][4][2], const pg8::Unit& u, int wr, int wc, int fr, int fq) const {
;     ...
;             for (int m = 0; m < 4; ++m) { bf16_t* rowp = O + (size_t)(row0 + ai * 128 + m * 16) * FF + col0; const float r = rt[ai * 128 + m * 16];
;                 const float rl = -r * LOG2E, r2 = r * r; unsigned w[4];
; #pragma unroll
;                 for (int n = 0; n < 2; ++n)
; #pragma unroll
;                     for (int h = 0; h < 2; ++h) { const f32x2v g = {acc[ai][0][m][n][2 * h], acc[ai][0][m][n][2 * h + 1]}, uu = {acc[ai][1][m][n][2 * h], acc[ai][1][m][n][2 * h + 1]};
;                         const f32x2v t = g * rl; f32x2v d = {__builtin_amdgcn_exp2f(t.x), __builtin_amdgcn_exp2f(t.y)}; d = d + 1.0f;
;                         const f32x2v q = {__builtin_amdgcn_rcpf(d.x), __builtin_amdgcn_rcpf(d.y)}; const f32x2v o = ((g * uu) * r2) * q;
;                         w[2 * n + h] = cvt_pk2(o.x, o.y); }
;                 u32x4 wv; wv.x = w[0]; wv.y = w[1]; wv.z = w[2]; wv.w = w[3];
;                 *(u32x4*)rowp = wv; }
	v_fma_f32 v170, v170, v232, v232
	v_fma_f32 v171, v171, v232, v232
	v_fma_f32 v172, v172, v232, v232
	v_fma_f32 v173, v173, v232, v232
	v_fma_f32 v174, v174, v232, v232
	v_fma_f32 v175, v175, v232, v232
	v_fma_f32 v176, v176, v232, v232
	v_fma_f32 v177, v177, v232, v232
	v_rcp_f32_e32 v170, v170
	v_rcp_f32_e32 v171, v171
	v_rcp_f32_e32 v172, v172
	v_rcp_f32_e32 v173, v173
	v_rcp_f32_e32 v174, v174
	v_rcp_f32_e32 v175, v175
	v_rcp_f32_e32 v176, v176
	v_rcp_f32_e32 v177, v177
	v_mul_f32_e32 v104, v104, v162
	v_mul_f32_e32 v105, v105, v163
	v_mul_f32_e32 v106, v106, v164
	v_mul_f32_e32 v107, v107, v165
	v_mul_f32_e32 v96, v96, v166
	v_mul_f32_e32 v97, v97, v167
	v_mul_f32_e32 v98, v98, v168
	v_mul_f32_e32 v99, v99, v169
	v_cvt_pk_bf16_f32 v162, v104, v105
	v_cvt_pk_bf16_f32 v163, v106, v107
	v_cvt_pk_bf16_f32 v164, v96, v97
	v_cvt_pk_bf16_f32 v165, v98, v99
	global_store_dwordx4 v[178:179], v[162:165], off
	v_lshl_add_u64 v[178:179], v[178:179], 0, s[98:99]
	s_nop 1
	v_mul_f32_e32 v162, v60, v216
	v_mul_f32_e32 v163, v61, v216
	v_mul_f32_e32 v164, v62, v216
	v_mul_f32_e32 v165, v63, v216
	v_mul_f32_e32 v166, v52, v216
	v_mul_f32_e32 v167, v53, v216
	v_mul_f32_e32 v168, v54, v216
	v_mul_f32_e32 v169, v55, v216
	v_exp_f32_e32 v162, v162
	v_exp_f32_e32 v163, v163
	v_exp_f32_e32 v164, v164
	v_exp_f32_e32 v165, v165
	v_exp_f32_e32 v166, v166
	v_exp_f32_e32 v167, v167
	v_exp_f32_e32 v168, v168
	v_exp_f32_e32 v169, v169
	v_mul_f32_e32 v72, v76, v72
	v_mul_f32_e32 v73, v77, v73
	v_mul_f32_e32 v74, v78, v74
	v_mul_f32_e32 v75, v79, v75
	v_mul_f32_e32 v64, v68, v64
	v_mul_f32_e32 v65, v69, v65
	v_mul_f32_e32 v66, v70, v66
	v_mul_f32_e32 v67, v71, v67
	v_fma_f32 v154, v154, v234, v234
	v_fma_f32 v155, v155, v234, v234
	v_fma_f32 v156, v156, v234, v234
	v_fma_f32 v157, v157, v234, v234
	v_fma_f32 v158, v158, v234, v234
	v_fma_f32 v159, v159, v234, v234
	v_fma_f32 v160, v160, v234, v234
	v_fma_f32 v161, v161, v234, v234
	v_rcp_f32_e32 v154, v154
	v_rcp_f32_e32 v155, v155
	v_rcp_f32_e32 v156, v156
	v_rcp_f32_e32 v157, v157
	v_rcp_f32_e32 v158, v158
	v_rcp_f32_e32 v159, v159
	v_rcp_f32_e32 v160, v160
	v_rcp_f32_e32 v161, v161
	v_mul_f32_e32 v88, v88, v170
	v_mul_f32_e32 v89, v89, v171
	v_mul_f32_e32 v90, v90, v172
	v_mul_f32_e32 v91, v91, v173
	v_mul_f32_e32 v80, v80, v174
	v_mul_f32_e32 v81, v81, v175
	v_mul_f32_e32 v82, v82, v176
	v_mul_f32_e32 v83, v83, v177
	v_cvt_pk_bf16_f32 v170, v88, v89
	v_cvt_pk_bf16_f32 v171, v90, v91
	v_cvt_pk_bf16_f32 v172, v80, v81
	v_cvt_pk_bf16_f32 v173, v82, v83
	global_store_dwordx4 v[178:179], v[170:173], off
	v_lshl_add_u64 v[178:179], v[178:179], 0, s[98:99]
	s_nop 1
	v_mul_f32_e32 v170, v44, v218
	v_mul_f32_e32 v171, v45, v218
	v_mul_f32_e32 v172, v46, v218
	v_mul_f32_e32 v173, v47, v218
	v_mul_f32_e32 v174, v36, v218
	v_mul_f32_e32 v175, v37, v218
	v_mul_f32_e32 v176, v38, v218
	v_mul_f32_e32 v177, v39, v218
	v_exp_f32_e32 v170, v170
	v_exp_f32_e32 v171, v171
	v_exp_f32_e32 v172, v172
	v_exp_f32_e32 v173, v173
	v_exp_f32_e32 v174, v174
	v_exp_f32_e32 v175, v175
	v_exp_f32_e32 v176, v176
	v_exp_f32_e32 v177, v177
	v_mul_f32_e32 v56, v60, v56
	v_mul_f32_e32 v57, v61, v57
	v_mul_f32_e32 v58, v62, v58
	v_mul_f32_e32 v59, v63, v59
	v_mul_f32_e32 v48, v52, v48
	v_mul_f32_e32 v49, v53, v49
	v_mul_f32_e32 v50, v54, v50
	v_mul_f32_e32 v51, v55, v51
	v_fma_f32 v162, v162, v236, v236
	v_fma_f32 v163, v163, v236, v236
	v_fma_f32 v164, v164, v236, v236
	v_fma_f32 v165, v165, v236, v236
	v_fma_f32 v166, v166, v236, v236
	v_fma_f32 v167, v167, v236, v236
	v_fma_f32 v168, v168, v236, v236
	v_fma_f32 v169, v169, v236, v236
	v_rcp_f32_e32 v162, v162
	v_rcp_f32_e32 v163, v163
	v_rcp_f32_e32 v164, v164
	v_rcp_f32_e32 v165, v165
	v_rcp_f32_e32 v166, v166
	v_rcp_f32_e32 v167, v167
	v_rcp_f32_e32 v168, v168
	v_rcp_f32_e32 v169, v169
	v_mul_f32_e32 v72, v72, v154
	v_mul_f32_e32 v73, v73, v155
	v_mul_f32_e32 v74, v74, v156
	v_mul_f32_e32 v75, v75, v157
	v_mul_f32_e32 v64, v64, v158
	v_mul_f32_e32 v65, v65, v159
	v_mul_f32_e32 v66, v66, v160
	v_mul_f32_e32 v67, v67, v161
	v_cvt_pk_bf16_f32 v154, v72, v73
	v_cvt_pk_bf16_f32 v155, v74, v75
	v_cvt_pk_bf16_f32 v156, v64, v65
	v_cvt_pk_bf16_f32 v157, v66, v67
	global_store_dwordx4 v[178:179], v[154:157], off
	v_lshl_add_u64 v[178:179], v[178:179], 0, s[100:101]
	s_nop 1
	v_mul_f32_e32 v154, v28, v220
	v_mul_f32_e32 v155, v29, v220
	v_mul_f32_e32 v156, v30, v220
	v_mul_f32_e32 v157, v31, v220
	v_mul_f32_e32 v158, v20, v220
	v_mul_f32_e32 v159, v21, v220
	v_mul_f32_e32 v160, v22, v220
	v_mul_f32_e32 v161, v23, v220
	v_exp_f32_e32 v154, v154
	v_exp_f32_e32 v155, v155
	v_exp_f32_e32 v156, v156
	v_exp_f32_e32 v157, v157
	v_exp_f32_e32 v158, v158
; #define PG8_BAR __builtin_amdgcn_s_barrier()
; __device__ __forceinline__ unsigned cvt_pk2(float lo, float hi) { f32x2c v = {lo, hi}; bf16x2c q = __builtin_convertvector(v, bf16x2c); return __builtin_bit_cast(unsigned, q); }
; template <class Epi, class Sched, bool ALIGN_EPI = false, bool SP2 = false>
; __device__ __forceinline__ void gemm_phase(PG8_LAS unsigned char* lds, const Gemm g, const Sched& S, const Epi& E) {
;     ...
;         if (!has_next) break;
; #pragma unroll
;         for (int a = 0; a < 2; ++a)
; #pragma unroll
;             for (int b = 0; b < 2; ++b)
; #pragma unroll
;                 for (int m = 0; m < 4; ++m)
; #pragma unroll
;                     for (int n = 0; n < 2; ++n) acc[a][b][m][n] = (f32x4){0.f, 0.f, 0.f, 0.f};
;         cur = nxt; cA = nA; cB = nB; ++ui;
;         if constexpr (ALIGN_EPI) { if (wr == 1) PG8_BAR; }
;     __device__ __forceinline__ void operator()(const f32x4 (&acc)[2][2][4][2], const pg8::Unit& u, int wr, int wc, int fr, int fq) const {
;     ...
;             for (int m = 0; m < 4; ++m) { bf16_t* rowp = O + (size_t)(row0 + ai * 128 + m * 16) * FF + col0; const float r = rt[ai * 128 + m * 16];
;                 const float rl = -r * LOG2E, r2 = r * r; unsigned w[4];
; #pragma unroll
;                 for (int n = 0; n < 2; ++n)
; #pragma unroll
;                     for (int h = 0; h < 2; ++h) { const f32x2v g = {acc[ai][0][m][n][2 * h], acc[ai][0][m][n][2 * h + 1]}, uu = {acc[ai][1][m][n][2 * h], acc[ai][1][m][n][2 * h + 1]};
;                         const f32x2v t = g * rl; f32x2v d = {__builtin_amdgcn_exp2f(t.x), __builtin_amdgcn_exp2f(t.y)}; d = d + 1.0f;
;                         const f32x2v q = {__builtin_amdgcn_rcpf(d.x), __builtin_amdgcn_rcpf(d.y)}; const f32x2v o = ((g * uu) * r2) * q;
;                         w[2 * n + h] = cvt_pk2(o.x, o.y); }
;                 u32x4 wv; wv.x = w[0]; wv.y = w[1]; wv.z = w[2]; wv.w = w[3];
;                 *(u32x4*)rowp = wv; }
	v_exp_f32_e32 v159, v159
	v_exp_f32_e32 v160, v160
	v_exp_f32_e32 v161, v161
	v_mul_f32_e32 v40, v44, v40
	v_mul_f32_e32 v41, v45, v41
	v_mul_f32_e32 v42, v46, v42
	v_mul_f32_e32 v43, v47, v43
	v_mul_f32_e32 v32, v36, v32
	v_mul_f32_e32 v33, v37, v33
	v_mul_f32_e32 v34, v38, v34
	v_mul_f32_e32 v35, v39, v35
	v_fma_f32 v170, v170, v238, v238
	v_fma_f32 v171, v171, v238, v238
	v_fma_f32 v172, v172, v238, v238
	v_fma_f32 v173, v173, v238, v238
	v_fma_f32 v174, v174, v238, v238
	v_fma_f32 v175, v175, v238, v238
	v_fma_f32 v176, v176, v238, v238
	v_fma_f32 v177, v177, v238, v238
	v_rcp_f32_e32 v170, v170
	v_rcp_f32_e32 v171, v171
	v_rcp_f32_e32 v172, v172
	v_rcp_f32_e32 v173, v173
	v_rcp_f32_e32 v174, v174
	v_rcp_f32_e32 v175, v175
	v_rcp_f32_e32 v176, v176
	v_rcp_f32_e32 v177, v177
	v_mul_f32_e32 v56, v56, v162
	v_mul_f32_e32 v57, v57, v163
	v_mul_f32_e32 v58, v58, v164
	v_mul_f32_e32 v59, v59, v165
	v_mul_f32_e32 v48, v48, v166
	v_mul_f32_e32 v49, v49, v167
	v_mul_f32_e32 v50, v50, v168
	v_mul_f32_e32 v51, v51, v169
	v_cvt_pk_bf16_f32 v162, v56, v57
	v_cvt_pk_bf16_f32 v163, v58, v59
	v_cvt_pk_bf16_f32 v164, v48, v49
	v_cvt_pk_bf16_f32 v165, v50, v51
	global_store_dwordx4 v[178:179], v[162:165], off
	v_lshl_add_u64 v[178:179], v[178:179], 0, s[98:99]
	s_nop 1
	v_mul_f32_e32 v162, v12, v222
	v_mul_f32_e32 v163, v13, v222
	v_mul_f32_e32 v164, v14, v222
	v_mul_f32_e32 v165, v15, v222
	v_mul_f32_e32 v166, v4, v222
	v_mul_f32_e32 v167, v5, v222
	v_mul_f32_e32 v168, v6, v222
	v_mul_f32_e32 v169, v7, v222
	v_exp_f32_e32 v162, v162
	v_exp_f32_e32 v163, v163
	v_exp_f32_e32 v164, v164
	v_exp_f32_e32 v165, v165
	v_exp_f32_e32 v166, v166
	v_exp_f32_e32 v167, v167
	v_exp_f32_e32 v168, v168
	v_exp_f32_e32 v169, v169
	v_mul_f32_e32 v24, v28, v24
	v_mul_f32_e32 v25, v29, v25
	v_mul_f32_e32 v26, v30, v26
	v_mul_f32_e32 v27, v31, v27
	v_mul_f32_e32 v16, v20, v16
	v_mul_f32_e32 v17, v21, v17
	v_mul_f32_e32 v18, v22, v18
	v_mul_f32_e32 v19, v23, v19
	v_fma_f32 v154, v154, v240, v240
	v_fma_f32 v155, v155, v240, v240
	v_fma_f32 v156, v156, v240, v240
	v_fma_f32 v157, v157, v240, v240
	v_fma_f32 v158, v158, v240, v240
	v_fma_f32 v159, v159, v240, v240
	v_fma_f32 v160, v160, v240, v240
	v_fma_f32 v161, v161, v240, v240
	v_rcp_f32_e32 v154, v154
	v_rcp_f32_e32 v155, v155
	v_rcp_f32_e32 v156, v156
	v_rcp_f32_e32 v157, v157
	v_rcp_f32_e32 v158, v158
	v_rcp_f32_e32 v159, v159
	v_rcp_f32_e32 v160, v160
	v_rcp_f32_e32 v161, v161
	v_mul_f32_e32 v40, v40, v170
	v_mul_f32_e32 v41, v41, v171
	v_mul_f32_e32 v42, v42, v172
	v_mul_f32_e32 v43, v43, v173
	v_mul_f32_e32 v32, v32, v174
	v_mul_f32_e32 v33, v33, v175
	v_mul_f32_e32 v34, v34, v176
	v_mul_f32_e32 v35, v35, v177
	v_cvt_pk_bf16_f32 v170, v40, v41
	v_cvt_pk_bf16_f32 v171, v42, v43
	v_cvt_pk_bf16_f32 v172, v32, v33
	v_cvt_pk_bf16_f32 v173, v34, v35
	global_store_dwordx4 v[178:179], v[170:173], off
	v_lshl_add_u64 v[178:179], v[178:179], 0, s[98:99]
	s_nop 1
	v_mul_f32_e32 v8, v12, v8
	v_mul_f32_e32 v9, v13, v9
	v_mul_f32_e32 v10, v14, v10
	v_mul_f32_e32 v11, v15, v11
	v_mul_f32_e32 v0, v4, v0
	v_mul_f32_e32 v1, v5, v1
	v_mul_f32_e32 v2, v6, v2
	v_mul_f32_e32 v3, v7, v3
	v_fma_f32 v162, v162, v242, v242
	v_fma_f32 v163, v163, v242, v242
	v_fma_f32 v164, v164, v242, v242
	v_fma_f32 v165, v165, v242, v242
	v_fma_f32 v166, v166, v242, v242
	v_fma_f32 v167, v167, v242, v242
	v_fma_f32 v168, v168, v242, v242
	v_fma_f32 v169, v169, v242, v242
	v_rcp_f32_e32 v162, v162
	v_rcp_f32_e32 v163, v163
	v_rcp_f32_e32 v164, v164
	v_rcp_f32_e32 v165, v165
	v_rcp_f32_e32 v166, v166
	v_rcp_f32_e32 v167, v167
	v_rcp_f32_e32 v168, v168
	v_rcp_f32_e32 v169, v169
	v_mul_f32_e32 v24, v24, v154
	v_mul_f32_e32 v25, v25, v155
	v_mul_f32_e32 v26, v26, v156
	v_mul_f32_e32 v27, v27, v157
	v_mul_f32_e32 v16, v16, v158
	v_mul_f32_e32 v17, v17, v159
	v_mul_f32_e32 v18, v18, v160
	v_mul_f32_e32 v19, v19, v161
	v_cvt_pk_bf16_f32 v154, v24, v25
	v_cvt_pk_bf16_f32 v155, v26, v27
	v_cvt_pk_bf16_f32 v156, v16, v17
	v_cvt_pk_bf16_f32 v157, v18, v19
	global_store_dwordx4 v[178:179], v[154:157], off
	v_lshl_add_u64 v[178:179], v[178:179], 0, s[98:99]
	s_nop 1
	v_mul_f32_e32 v8, v8, v162
	v_mul_f32_e32 v9, v9, v163
	v_mul_f32_e32 v10, v10, v164
	v_mul_f32_e32 v11, v11, v165
	v_mul_f32_e32 v0, v0, v166
	v_mul_f32_e32 v1, v1, v167
	v_mul_f32_e32 v2, v2, v168
	v_mul_f32_e32 v3, v3, v169
	v_cvt_pk_bf16_f32 v162, v8, v9
	v_cvt_pk_bf16_f32 v163, v10, v11
	v_cvt_pk_bf16_f32 v164, v0, v1
	v_cvt_pk_bf16_f32 v165, v2, v3
	global_store_dwordx4 v[178:179], v[162:165], off
	s_andn2_b64 vcc, exec, s[4:5]
	s_mov_b64 s[4:5], -1
	s_cbranch_vccnz .LBB0_1736
	s_andn2_b64 vcc, exec, s[0:1]
	s_cbranch_vccnz .LBB0_1735
	s_barrier
	s_branch .LBB0_1735
